# attention: running softmax reference kept replicated in 16 spare VGPRs and fed as SrcC of the first QK MFMA (drops a 23-instruction v_mov chain per 32-key sub-step)
# speedup vs baseline: 1.0076x; 1.0076x over previous
; #define MFMA32(a, b, c) __builtin_amdgcn_mfma_f32_32x32x16_bf16((a), (b), (c), 0, 0, 0)
; __device__ __forceinline__ void attn_phase(const Args& a, int l, bool with_ctx, unsigned char* lds) {
;     ...
;         const int qpos = qbase + qsub * 32 + r32;
;         bf16x8 qf[4];
;         { const bf16_t* Qb = Qr + ((size_t)(bh * 2 + c) * KVL + qpos) * 64 + 8 * hi;
; #pragma unroll
;           for (int d0 = 0; d0 < 4; ++d0) qf[d0] = *(const bf16x8*)(Qb + 16 * d0); }
;         f32x16 O[4];
; #pragma unroll
;         for (int j = 0; j < 4; ++j)
; #pragma unroll
;             for (int r = 0; r < 16; ++r) O[j][r] = 0.f;
;         float negm = 0.f, lrun = 0.f; bool first = true;
;         u32x4 k0 = *(const u32x4*)Kg0, k1 = *(const u32x4*)Kg1, v0 = *(const u32x4*)Vg0, v1 = *(const u32x4*)Vg1;
;         __syncthreads();
;         *(u32x4*)kdst = k0; *(u32x4*)(kdst + 9216) = k1; *(u32x4*)vdst = v0; *(u32x4*)(vdst + 9216) = v1;
;         __syncthreads();
;         const int nt = nkv >> 6;
;         for (int t = 0; t < nt; ++t) {
;             const int cur = t & 1;
;             if (t + 1 < nt) { k0 = *(const u32x4*)(Kg0 + (size_t)(t + 1) * 64 * 64); k1 = *(const u32x4*)(Kg1 + (size_t)(t + 1) * 64 * 64);
;                               v0 = *(const u32x4*)(Vg0 + (t + 1) * 64); v1 = *(const u32x4*)(Vg1 + (t + 1) * 64); }
; #pragma unroll
;             for (int sub = 0; sub < 2; ++sub) {
;                 const unsigned char* kb = lds + cur * BUF + c * 9216 + (32 * sub + r32) * 144 + hi * 16;
;                 const unsigned char* vb = lds + cur * BUF + KT + r32 * 144 + 64 * sub + hi * 16;
;                 bf16x8 kf[4], vf[8];
; #pragma unroll
;                 for (int d0 = 0; d0 < 4; ++d0) kf[d0] = *(const bf16x8*)(kb + d0 * 32);
; #pragma unroll
;                 for (int j = 0; j < 4; ++j) { vf[2 * j] = *(const bf16x8*)(vb + j * 32 * 144); vf[2 * j + 1] = *(const bf16x8*)(vb + j * 32 * 144 + 32); }
;                 __builtin_amdgcn_sched_barrier(0);
;                 f32x16 S;
; #pragma unroll
;                 for (int r = 0; r < 16; ++r) S[r] = negm;
; #pragma unroll
;                 for (int d0 = 0; d0 < 4; ++d0) S = MFMA32(kf[d0], qf[d0], S);
;                 float mx = S[0];
; #pragma unroll
;                 for (int r = 1; r < 16; ++r) mx = fmaxf(mx, S[r]);
;                 if (first || __any(mx > 8.f)) {
;                     mx = fmaxf(mx, __shfl_xor(mx, 32));
.LBB0_403:
	s_or_b32 s7, s6, s17
	s_lshl_b32 s8, s7, 7
	s_and_b32 s8, s8, 0xf80
	s_addk_i32 s8, 0x100
	s_lshl_b32 s9, s6, 7
	s_cmpk_lt_i32 s7, 0x200
	s_cselect_b64 s[14:15], -1, 0
	s_and_b64 s[6:7], s[14:15], exec
	s_cselect_b32 s6, s21, s20
	s_cselect_b32 s23, s8, s9
	s_lshl_b32 s22, s6, 1
	v_mov_b32_e32 v2, 0x1100
	v_mad_i64_i32 v[2:3], s[8:9], s22, v2, v[152:153]
	s_ashr_i32 s7, s6, 31
	v_lshlrev_b64 v[2:3], 7, v[2:3]
	s_lshl_b64 s[8:9], s[6:7], 7
	v_lshl_add_u64 v[18:19], v[156:157], 0, v[2:3]
	v_lshl_add_u64 v[2:3], s[8:9], 0, v[152:153]
	v_add_u32_e32 v170, s23, v177
	v_mad_u64_u32 v[20:21], s[8:9], v2, s66, v[158:159]
	v_or_b32_e32 v2, s22, v149
	v_ashrrev_i32_e32 v171, 31, v170
	v_mad_i32_i24 v21, v3, s66, v21
	v_mad_i64_i32 v[2:3], s[8:9], v2, s73, v[170:171]
	v_lshlrev_b64 v[2:3], 7, v[2:3]
	v_add_co_u32_e32 v6, vcc, s67, v18
	v_lshl_add_u64 v[2:3], v[162:163], 0, v[2:3]
	s_nop 0
	v_addc_co_u32_e32 v7, vcc, 0, v19, vcc
	global_load_dwordx4 v[84:87], v[2:3], off
	global_load_dwordx4 v[88:91], v[2:3], off offset:32
	global_load_dwordx4 v[92:95], v[2:3], off offset:64
	global_load_dwordx4 v[96:99], v[2:3], off offset:96
	s_nop 0
	global_load_dwordx4 v[2:5], v[18:19], off
	s_nop 0
	global_load_dwordx4 v[6:9], v[6:7], off
	s_nop 0
	global_load_dwordx4 v[10:13], v[20:21], off
	v_add_co_u32_e32 v22, vcc, s67, v20
	s_mov_b32 s7, 0x8a000
	s_nop 0
	v_addc_co_u32_e32 v23, vcc, 0, v21, vcc
	global_load_dwordx4 v[14:17], v[22:23], off
	s_barrier
	s_waitcnt vmcnt(3)
	ds_write_b128 v176, v[2:5]
	s_waitcnt vmcnt(2)
	ds_write_b128 v176, v[6:9] offset:9216
	s_waitcnt vmcnt(1)
	ds_write_b128 v176, v[10:13] offset:18432
	s_waitcnt vmcnt(0)
	ds_write_b128 v176, v[14:17] offset:27648
	v_add_co_u32_e32 v2, vcc, s70, v18
	s_waitcnt lgkmcnt(0)
	s_nop 0
	v_addc_co_u32_e32 v3, vcc, 0, v19, vcc
	s_barrier
	global_load_dwordx4 v[100:103], v[2:3], off
	v_add_co_u32_e32 v2, vcc, s7, v18
	s_nop 1
	v_addc_co_u32_e32 v3, vcc, 0, v19, vcc
	global_load_dwordx4 v[104:107], v[2:3], off
	global_load_dwordx4 v[108:111], v[20:21], off offset:128
	global_load_dwordx4 v[112:115], v[22:23], off offset:128
	ds_read_b128 v[2:5], v161
	ds_read_b128 v[18:21], v161 offset:32
	ds_read_b128 v[22:25], v161 offset:64
	ds_read_b128 v[26:29], v161 offset:96
	ds_read_b128 v[30:33], v183 offset:18432
	ds_read_b128 v[80:83], v183 offset:18464
	ds_read_b128 v[34:37], v183 offset:23040
	ds_read_b128 v[68:71], v183 offset:23072
	ds_read_b128 v[116:119], v183 offset:27648
	ds_read_b128 v[72:75], v183 offset:27680
	ds_read_b128 v[120:123], v183 offset:32256
	ds_read_b128 v[76:79], v183 offset:32288
	s_waitcnt lgkmcnt(11)
	v_mfma_f32_32x32x16_bf16 v[2:17], v[2:5], v[84:87], 0
	s_waitcnt lgkmcnt(10)
	v_mfma_f32_32x32x16_bf16 v[2:17], v[18:21], v[88:91], v[2:17]
	s_waitcnt lgkmcnt(9)
	v_mfma_f32_32x32x16_bf16 v[2:17], v[22:25], v[92:95], v[2:17]
	s_waitcnt lgkmcnt(8)
	v_mfma_f32_32x32x16_bf16 v[2:17], v[26:29], v[96:99], v[2:17]
	s_nop 11
	v_max_f32_e32 v18, v3, v3
	v_max_f32_e32 v19, v2, v2
	v_max_f32_e32 v18, v19, v18
	v_max3_f32 v18, v18, v4, v5
	v_max3_f32 v18, v18, v6, v7
	v_max3_f32 v18, v18, v8, v9
	v_max3_f32 v18, v18, v10, v11
	v_max3_f32 v18, v18, v12, v13
	v_max3_f32 v18, v18, v14, v15
	v_max3_f32 v18, v18, v16, v17
	ds_bpermute_b32 v19, v180, v18
	s_waitcnt lgkmcnt(0)
	v_max_f32_e32 v19, v19, v19
	v_max_f32_e32 v18, v18, v19
	v_sub_f32_e32 v2, v2, v18
	v_sub_f32_e32 v3, v3, v18
	v_exp_f32_e32 v67, v2
	v_exp_f32_e32 v128, v3
	v_sub_f32_e32 v4, v4, v18
	v_sub_f32_e32 v5, v5, v18
	v_exp_f32_e32 v129, v4
	v_sub_f32_e32 v6, v6, v18
	v_exp_f32_e32 v130, v5
	v_sub_f32_e32 v7, v7, v18
	v_exp_f32_e32 v131, v6
	v_cvt_pk_bf16_f32 v2, v67, v128
	v_add_f32_e32 v67, 0, v67
	v_sub_f32_e32 v8, v8, v18
	v_sub_f32_e32 v9, v9, v18
	v_exp_f32_e32 v132, v7
	v_add_f32_e32 v67, v128, v67
	v_exp_f32_e32 v133, v8
	v_exp_f32_e32 v134, v9
	v_add_f32_e32 v67, v129, v67
	v_sub_f32_e32 v10, v10, v18
	v_add_f32_e32 v67, v130, v67
	v_sub_f32_e32 v11, v11, v18
	v_exp_f32_e32 v135, v10
	v_add_f32_e32 v67, v131, v67
	v_sub_f32_e32 v12, v12, v18
	v_exp_f32_e32 v136, v11
	v_add_f32_e32 v67, v132, v67
	v_sub_f32_e32 v13, v13, v18
	v_sub_f32_e32 v14, v14, v18
	v_sub_f32_e32 v15, v15, v18
	v_sub_f32_e32 v16, v16, v18
	v_sub_f32_e32 v17, v17, v18
	v_exp_f32_e32 v137, v12
	v_cvt_pk_bf16_f32 v3, v129, v130
	v_cvt_pk_bf16_f32 v4, v131, v132
	v_cvt_pk_bf16_f32 v5, v133, v134
	v_add_f32_e32 v67, v133, v67
	v_sub_f32_e32 v66, 0, v18
	v_mov_b32_e32 v230, v66
	v_mov_b32_e32 v231, v66
	v_mov_b32_e32 v232, v66
	v_mov_b32_e32 v233, v66
	v_mov_b32_e32 v234, v66
	v_mov_b32_e32 v235, v66
	v_mov_b32_e32 v236, v66
	v_mov_b32_e32 v237, v66
	v_mov_b32_e32 v238, v66
	v_mov_b32_e32 v239, v66
	v_mov_b32_e32 v240, v66
	v_mov_b32_e32 v241, v66
	v_mov_b32_e32 v242, v66
	v_mov_b32_e32 v243, v66
	v_mov_b32_e32 v244, v66
	v_mov_b32_e32 v245, v66
	v_exp_f32_e32 v138, v13
	v_exp_f32_e32 v139, v14
	v_exp_f32_e32 v140, v15
	v_exp_f32_e32 v141, v16
	v_exp_f32_e32 v142, v17
	v_mfma_f32_32x32x16_bf16 v[50:65], v[30:33], v[2:5], 0
	v_add_f32_e32 v67, v134, v67
	v_add_f32_e32 v67, v135, v67
	v_add_f32_e32 v67, v136, v67
	v_add_f32_e32 v67, v137, v67
	v_add_f32_e32 v67, v138, v67
	v_add_f32_e32 v67, v139, v67
	v_add_f32_e32 v67, v140, v67
	v_mfma_f32_32x32x16_bf16 v[34:49], v[34:37], v[2:5], 0
	v_cvt_pk_bf16_f32 v124, v135, v136
	v_cvt_pk_bf16_f32 v125, v137, v138
	v_cvt_pk_bf16_f32 v126, v139, v140
	v_cvt_pk_bf16_f32 v127, v141, v142
	v_add_f32_e32 v67, v141, v67
	v_add_f32_e32 v67, v142, v67
	v_add_f32_e32 v171, 0, v67
	v_mfma_f32_32x32x16_bf16 v[18:33], v[116:119], v[2:5], 0
	v_mfma_f32_32x32x16_bf16 v[2:17], v[120:123], v[2:5], 0
	v_mfma_f32_32x32x16_bf16 v[50:65], v[80:83], v[124:127], v[50:65]
	v_mfma_f32_32x32x16_bf16 v[34:49], v[68:71], v[124:127], v[34:49]
	v_mfma_f32_32x32x16_bf16 v[18:33], v[72:75], v[124:127], v[18:33]
	v_mfma_f32_32x32x16_bf16 v[2:17], v[76:79], v[124:127], v[2:17]
	ds_read_b128 v[172:175], v161 offset:4608
	ds_read_b128 v[184:187], v161 offset:4640
	ds_read_b128 v[214:217], v161 offset:4672
	ds_read_b128 v[218:221], v161 offset:4704
	ds_read_b128 v[144:147], v183 offset:18496
	ds_read_b128 v[128:131], v183 offset:18528
	ds_read_b128 v[140:143], v183 offset:23104
	ds_read_b128 v[116:119], v183 offset:23136
	ds_read_b128 v[136:139], v183 offset:27712
	ds_read_b128 v[120:123], v183 offset:27744
	ds_read_b128 v[132:135], v183 offset:32320
	ds_read_b128 v[124:127], v183 offset:32352
	s_waitcnt lgkmcnt(11)
; #define MFMA32(a, b, c) __builtin_amdgcn_mfma_f32_32x32x16_bf16((a), (b), (c), 0, 0, 0)
; __device__ __forceinline__ void attn_phase(const Args& a, int l, bool with_ctx, unsigned char* lds) {
;     ...
;                 for (int d0 = 0; d0 < 4; ++d0) kf[d0] = *(const bf16x8*)(kb + d0 * 32);
; #pragma unroll
;                 for (int j = 0; j < 4; ++j) { vf[2 * j] = *(const bf16x8*)(vb + j * 32 * 144); vf[2 * j + 1] = *(const bf16x8*)(vb + j * 32 * 144 + 32); }
;                 __builtin_amdgcn_sched_barrier(0);
;                 f32x16 S;
; #pragma unroll
;                 for (int r = 0; r < 16; ++r) S[r] = negm;
; #pragma unroll
;                 for (int d0 = 0; d0 < 4; ++d0) S = MFMA32(kf[d0], qf[d0], S);
;                 float mx = S[0];
; #pragma unroll
;                 for (int r = 1; r < 16; ++r) mx = fmaxf(mx, S[r]);
;                 if (first || __any(mx > 8.f)) {
;                     mx = fmaxf(mx, __shfl_xor(mx, 32));
;                     const float dl = first ? mx : fmaxf(mx, 0.f); const float alpha = first ? 1.f : __builtin_amdgcn_exp2f(-dl); negm -= dl; lrun *= alpha; first = false;
; #pragma unroll
;                     for (int r = 0; r < 16; ++r) S[r] -= dl;
; #pragma unroll
;                     for (int j = 0; j < 4; ++j)
; #pragma unroll
;                         for (int r = 0; r < 16; ++r) O[j][r] *= alpha;
	s_nop 0
	v_mfma_f32_32x32x16_bf16 v[68:83], v[172:175], v[84:87], v[230:245]
	s_waitcnt lgkmcnt(10)
	v_mfma_f32_32x32x16_bf16 v[68:83], v[184:187], v[88:91], v[68:83]
	s_waitcnt lgkmcnt(9)
	v_mfma_f32_32x32x16_bf16 v[68:83], v[214:217], v[92:95], v[68:83]
	s_waitcnt lgkmcnt(8)
	v_mfma_f32_32x32x16_bf16 v[68:83], v[218:221], v[96:99], v[68:83]
	s_nop 11
	v_max_f32_e32 v67, v69, v69
	v_max_f32_e32 v172, v68, v68
	v_max_f32_e32 v67, v172, v67
	v_max3_f32 v67, v67, v70, v71
	v_max3_f32 v67, v67, v72, v73
	v_max3_f32 v67, v67, v74, v75
	v_max3_f32 v67, v67, v76, v77
	v_max3_f32 v67, v67, v78, v79
	v_max3_f32 v67, v67, v80, v81
	v_max3_f32 v67, v67, v82, v83
	v_cmp_lt_f32_e32 vcc, s68, v67
	s_cbranch_vccz .LBB0_405
	ds_bpermute_b32 v172, v180, v67
	s_waitcnt lgkmcnt(0)
	v_max3_f32 v172, v67, v172, 0
	v_exp_f32_e64 v174, -v172
	v_sub_f32_e32 v66, v66, v172
	v_mov_b32_e32 v230, v66
	v_mov_b32_e32 v231, v66
	v_mov_b32_e32 v232, v66
	v_mov_b32_e32 v233, v66
	v_mov_b32_e32 v234, v66
	v_mov_b32_e32 v235, v66
	v_mov_b32_e32 v236, v66
	v_mov_b32_e32 v237, v66
	v_mov_b32_e32 v238, v66
	v_mov_b32_e32 v239, v66
	v_mov_b32_e32 v240, v66
	v_mov_b32_e32 v241, v66
	v_mov_b32_e32 v242, v66
	v_mov_b32_e32 v243, v66
	v_mov_b32_e32 v244, v66
	v_mov_b32_e32 v245, v66
	v_pk_add_f32 v[68:69], v[68:69], v[172:173] op_sel_hi:[1,0] neg_lo:[0,1] neg_hi:[0,1]
	v_pk_add_f32 v[70:71], v[70:71], v[172:173] op_sel_hi:[1,0] neg_lo:[0,1] neg_hi:[0,1]
	v_pk_add_f32 v[72:73], v[72:73], v[172:173] op_sel_hi:[1,0] neg_lo:[0,1] neg_hi:[0,1]
	v_pk_add_f32 v[74:75], v[74:75], v[172:173] op_sel_hi:[1,0] neg_lo:[0,1] neg_hi:[0,1]
	v_pk_add_f32 v[76:77], v[76:77], v[172:173] op_sel_hi:[1,0] neg_lo:[0,1] neg_hi:[0,1]
	v_pk_add_f32 v[78:79], v[78:79], v[172:173] op_sel_hi:[1,0] neg_lo:[0,1] neg_hi:[0,1]
	v_pk_add_f32 v[80:81], v[80:81], v[172:173] op_sel_hi:[1,0] neg_lo:[0,1] neg_hi:[0,1]
	v_pk_add_f32 v[82:83], v[82:83], v[172:173] op_sel_hi:[1,0] neg_lo:[0,1] neg_hi:[0,1]
	v_pk_mul_f32 v[64:65], v[64:65], v[174:175] op_sel_hi:[1,0]
	v_pk_mul_f32 v[62:63], v[62:63], v[174:175] op_sel_hi:[1,0]
	v_pk_mul_f32 v[60:61], v[60:61], v[174:175] op_sel_hi:[1,0]
	v_pk_mul_f32 v[58:59], v[58:59], v[174:175] op_sel_hi:[1,0]
	v_pk_mul_f32 v[56:57], v[56:57], v[174:175] op_sel_hi:[1,0]
	v_pk_mul_f32 v[54:55], v[54:55], v[174:175] op_sel_hi:[1,0]
	v_pk_mul_f32 v[52:53], v[52:53], v[174:175] op_sel_hi:[1,0]
	v_pk_mul_f32 v[50:51], v[50:51], v[174:175] op_sel_hi:[1,0]
	v_pk_mul_f32 v[48:49], v[48:49], v[174:175] op_sel_hi:[1,0]
	v_pk_mul_f32 v[46:47], v[46:47], v[174:175] op_sel_hi:[1,0]
	v_pk_mul_f32 v[44:45], v[44:45], v[174:175] op_sel_hi:[1,0]
	v_pk_mul_f32 v[42:43], v[42:43], v[174:175] op_sel_hi:[1,0]
	v_pk_mul_f32 v[40:41], v[40:41], v[174:175] op_sel_hi:[1,0]
	v_pk_mul_f32 v[38:39], v[38:39], v[174:175] op_sel_hi:[1,0]
	v_pk_mul_f32 v[36:37], v[36:37], v[174:175] op_sel_hi:[1,0]
	v_pk_mul_f32 v[34:35], v[34:35], v[174:175] op_sel_hi:[1,0]
	v_pk_mul_f32 v[32:33], v[32:33], v[174:175] op_sel_hi:[1,0]
	v_pk_mul_f32 v[30:31], v[30:31], v[174:175] op_sel_hi:[1,0]
	v_pk_mul_f32 v[28:29], v[28:29], v[174:175] op_sel_hi:[1,0]
	v_pk_mul_f32 v[26:27], v[26:27], v[174:175] op_sel_hi:[1,0]
	v_pk_mul_f32 v[24:25], v[24:25], v[174:175] op_sel_hi:[1,0]
	v_pk_mul_f32 v[22:23], v[22:23], v[174:175] op_sel_hi:[1,0]
	v_pk_mul_f32 v[20:21], v[20:21], v[174:175] op_sel_hi:[1,0]
	v_pk_mul_f32 v[18:19], v[18:19], v[174:175] op_sel_hi:[1,0]
	v_pk_mul_f32 v[16:17], v[16:17], v[174:175] op_sel_hi:[1,0]
	v_pk_mul_f32 v[14:15], v[14:15], v[174:175] op_sel_hi:[1,0]
	v_pk_mul_f32 v[12:13], v[12:13], v[174:175] op_sel_hi:[1,0]
	v_pk_mul_f32 v[10:11], v[10:11], v[174:175] op_sel_hi:[1,0]
	v_pk_mul_f32 v[8:9], v[8:9], v[174:175] op_sel_hi:[1,0]
	v_pk_mul_f32 v[6:7], v[6:7], v[174:175] op_sel_hi:[1,0]
	v_pk_mul_f32 v[4:5], v[4:5], v[174:175] op_sel_hi:[1,0]
	v_pk_mul_f32 v[2:3], v[2:3], v[174:175] op_sel_hi:[1,0]
	v_mul_f32_e32 v171, v171, v174

; #define MFMA32(a, b, c) __builtin_amdgcn_mfma_f32_32x32x16_bf16((a), (b), (c), 0, 0, 0)
; __device__ __forceinline__ void attn_phase(const Args& a, int l, bool with_ctx, unsigned char* lds) {
;     ...
;                 const unsigned char* kb = lds + cur * BUF + c * 9216 + (32 * sub + r32) * 144 + hi * 16;
;                 const unsigned char* vb = lds + cur * BUF + KT + r32 * 144 + 64 * sub + hi * 16;
;                 bf16x8 kf[4], vf[8];
; #pragma unroll
;                 for (int d0 = 0; d0 < 4; ++d0) kf[d0] = *(const bf16x8*)(kb + d0 * 32);
; #pragma unroll
;                 for (int j = 0; j < 4; ++j) { vf[2 * j] = *(const bf16x8*)(vb + j * 32 * 144); vf[2 * j + 1] = *(const bf16x8*)(vb + j * 32 * 144 + 32); }
;                 __builtin_amdgcn_sched_barrier(0);
;                 f32x16 S;
; #pragma unroll
;                 for (int r = 0; r < 16; ++r) S[r] = negm;
; #pragma unroll
;                 for (int d0 = 0; d0 < 4; ++d0) S = MFMA32(kf[d0], qf[d0], S);
;                 float mx = S[0];
; #pragma unroll
;                 for (int r = 1; r < 16; ++r) mx = fmaxf(mx, S[r]);
;                 if (first || __any(mx > 8.f)) {
;                     mx = fmaxf(mx, __shfl_xor(mx, 32));
;                     const float dl = first ? mx : fmaxf(mx, 0.f); const float alpha = first ? 1.f : __builtin_amdgcn_exp2f(-dl); negm -= dl; lrun *= alpha; first = false;
; #pragma unroll
;                     for (int r = 0; r < 16; ++r) S[r] -= dl;
; #pragma unroll
;                     for (int j = 0; j < 4; ++j)
; #pragma unroll
;                         for (int r = 0; r < 16; ++r) O[j][r] *= alpha;
.LBB0_408:
	s_and_b32 s15, s15, 1
	s_mul_i32 s22, s15, 0x9000
	s_add_i32 s22, s22, 0
	v_add3_u32 v67, s22, v178, v160
	v_add_u32_e32 v68, s22, v179
	v_add_u32_e32 v185, v67, v179
	v_add_u32_e32 v184, v68, v160
	ds_read_b128 v[214:217], v185
	ds_read_b128 v[218:221], v185 offset:32
	ds_read_b128 v[222:225], v185 offset:64
	ds_read_b128 v[226:229], v185 offset:96
	ds_read_b128 v[140:143], v184 offset:18432
	ds_read_b128 v[128:131], v184 offset:18464
	ds_read_b128 v[144:147], v184 offset:23040
	ds_read_b128 v[116:119], v184 offset:23072
	ds_read_b128 v[136:139], v184 offset:27648
	ds_read_b128 v[120:123], v184 offset:27680
	ds_read_b128 v[132:135], v184 offset:32256
	ds_read_b128 v[124:127], v184 offset:32288
	s_waitcnt lgkmcnt(11)
	s_nop 0
	v_mfma_f32_32x32x16_bf16 v[68:83], v[214:217], v[84:87], v[230:245]
	s_waitcnt lgkmcnt(10)
	v_mfma_f32_32x32x16_bf16 v[68:83], v[218:221], v[88:91], v[68:83]
	s_waitcnt lgkmcnt(9)
	v_mfma_f32_32x32x16_bf16 v[68:83], v[222:225], v[92:95], v[68:83]
	s_waitcnt lgkmcnt(8)
	v_mfma_f32_32x32x16_bf16 v[68:83], v[226:229], v[96:99], v[68:83]
	s_nop 11
	v_max_f32_e32 v67, v69, v69
	v_max_f32_e32 v186, v68, v68
	v_max_f32_e32 v67, v186, v67
	v_max3_f32 v67, v67, v70, v71
	v_max3_f32 v67, v67, v72, v73
	v_max3_f32 v67, v67, v74, v75
	v_max3_f32 v67, v67, v76, v77
	v_max3_f32 v67, v67, v78, v79
	v_max3_f32 v67, v67, v80, v81
	v_max3_f32 v67, v67, v82, v83
	v_cmp_lt_f32_e32 vcc, s68, v67
	s_cbranch_vccz .LBB0_410
	ds_bpermute_b32 v186, v180, v67
	s_waitcnt lgkmcnt(0)
	v_max3_f32 v186, v67, v186, 0
	v_exp_f32_e64 v214, -v186
	v_sub_f32_e32 v66, v66, v186
	v_mov_b32_e32 v230, v66
	v_mov_b32_e32 v231, v66
	v_mov_b32_e32 v232, v66
	v_mov_b32_e32 v233, v66
	v_mov_b32_e32 v234, v66
	v_mov_b32_e32 v235, v66
	v_mov_b32_e32 v236, v66
	v_mov_b32_e32 v237, v66
	v_mov_b32_e32 v238, v66
	v_mov_b32_e32 v239, v66
	v_mov_b32_e32 v240, v66
	v_mov_b32_e32 v241, v66
	v_mov_b32_e32 v242, v66
	v_mov_b32_e32 v243, v66
	v_mov_b32_e32 v244, v66
	v_mov_b32_e32 v245, v66
	v_pk_add_f32 v[68:69], v[68:69], v[186:187] op_sel_hi:[1,0] neg_lo:[0,1] neg_hi:[0,1]
	v_pk_add_f32 v[70:71], v[70:71], v[186:187] op_sel_hi:[1,0] neg_lo:[0,1] neg_hi:[0,1]
	v_pk_add_f32 v[72:73], v[72:73], v[186:187] op_sel_hi:[1,0] neg_lo:[0,1] neg_hi:[0,1]
	v_pk_add_f32 v[74:75], v[74:75], v[186:187] op_sel_hi:[1,0] neg_lo:[0,1] neg_hi:[0,1]
	v_pk_add_f32 v[76:77], v[76:77], v[186:187] op_sel_hi:[1,0] neg_lo:[0,1] neg_hi:[0,1]
	v_pk_add_f32 v[78:79], v[78:79], v[186:187] op_sel_hi:[1,0] neg_lo:[0,1] neg_hi:[0,1]
	v_pk_add_f32 v[80:81], v[80:81], v[186:187] op_sel_hi:[1,0] neg_lo:[0,1] neg_hi:[0,1]
	v_pk_add_f32 v[82:83], v[82:83], v[186:187] op_sel_hi:[1,0] neg_lo:[0,1] neg_hi:[0,1]
	v_pk_mul_f32 v[64:65], v[64:65], v[214:215] op_sel_hi:[1,0]
	v_pk_mul_f32 v[62:63], v[62:63], v[214:215] op_sel_hi:[1,0]
	v_pk_mul_f32 v[60:61], v[60:61], v[214:215] op_sel_hi:[1,0]
	v_pk_mul_f32 v[58:59], v[58:59], v[214:215] op_sel_hi:[1,0]
	v_pk_mul_f32 v[56:57], v[56:57], v[214:215] op_sel_hi:[1,0]
	v_pk_mul_f32 v[54:55], v[54:55], v[214:215] op_sel_hi:[1,0]
	v_pk_mul_f32 v[52:53], v[52:53], v[214:215] op_sel_hi:[1,0]
	v_pk_mul_f32 v[50:51], v[50:51], v[214:215] op_sel_hi:[1,0]
	v_pk_mul_f32 v[48:49], v[48:49], v[214:215] op_sel_hi:[1,0]
	v_pk_mul_f32 v[46:47], v[46:47], v[214:215] op_sel_hi:[1,0]
	v_pk_mul_f32 v[44:45], v[44:45], v[214:215] op_sel_hi:[1,0]
	v_pk_mul_f32 v[42:43], v[42:43], v[214:215] op_sel_hi:[1,0]
	v_pk_mul_f32 v[40:41], v[40:41], v[214:215] op_sel_hi:[1,0]
	v_pk_mul_f32 v[38:39], v[38:39], v[214:215] op_sel_hi:[1,0]
	v_pk_mul_f32 v[36:37], v[36:37], v[214:215] op_sel_hi:[1,0]
	v_pk_mul_f32 v[34:35], v[34:35], v[214:215] op_sel_hi:[1,0]
	v_pk_mul_f32 v[32:33], v[32:33], v[214:215] op_sel_hi:[1,0]
	v_pk_mul_f32 v[30:31], v[30:31], v[214:215] op_sel_hi:[1,0]
	v_pk_mul_f32 v[28:29], v[28:29], v[214:215] op_sel_hi:[1,0]
	v_pk_mul_f32 v[26:27], v[26:27], v[214:215] op_sel_hi:[1,0]
	v_pk_mul_f32 v[24:25], v[24:25], v[214:215] op_sel_hi:[1,0]
	v_pk_mul_f32 v[22:23], v[22:23], v[214:215] op_sel_hi:[1,0]
	v_pk_mul_f32 v[20:21], v[20:21], v[214:215] op_sel_hi:[1,0]
	v_pk_mul_f32 v[18:19], v[18:19], v[214:215] op_sel_hi:[1,0]
	v_pk_mul_f32 v[16:17], v[16:17], v[214:215] op_sel_hi:[1,0]
	v_pk_mul_f32 v[14:15], v[14:15], v[214:215] op_sel_hi:[1,0]
	v_pk_mul_f32 v[12:13], v[12:13], v[214:215] op_sel_hi:[1,0]
	v_pk_mul_f32 v[10:11], v[10:11], v[214:215] op_sel_hi:[1,0]
	v_pk_mul_f32 v[8:9], v[8:9], v[214:215] op_sel_hi:[1,0]
	v_pk_mul_f32 v[6:7], v[6:7], v[214:215] op_sel_hi:[1,0]
	v_pk_mul_f32 v[4:5], v[4:5], v[214:215] op_sel_hi:[1,0]
	v_pk_mul_f32 v[2:3], v[2:3], v[214:215] op_sel_hi:[1,0]
	v_mul_f32_e32 v171, v171, v214
; #define MFMA32(a, b, c) __builtin_amdgcn_mfma_f32_32x32x16_bf16((a), (b), (c), 0, 0, 0)
; __device__ __forceinline__ void attn_phase(const Args& a, int l, bool with_ctx, unsigned char* lds) {
;     ...
;                 const unsigned char* kb = lds + cur * BUF + c * 9216 + (32 * sub + r32) * 144 + hi * 16;
;                 const unsigned char* vb = lds + cur * BUF + KT + r32 * 144 + 64 * sub + hi * 16;
;                 bf16x8 kf[4], vf[8];
; #pragma unroll
;                 for (int d0 = 0; d0 < 4; ++d0) kf[d0] = *(const bf16x8*)(kb + d0 * 32);
; #pragma unroll
;                 for (int j = 0; j < 4; ++j) { vf[2 * j] = *(const bf16x8*)(vb + j * 32 * 144); vf[2 * j + 1] = *(const bf16x8*)(vb + j * 32 * 144 + 32); }
;                 __builtin_amdgcn_sched_barrier(0);
;                 f32x16 S;
; #pragma unroll
;                 for (int r = 0; r < 16; ++r) S[r] = negm;
; #pragma unroll
;                 for (int d0 = 0; d0 < 4; ++d0) S = MFMA32(kf[d0], qf[d0], S);
;                 float mx = S[0];
; #pragma unroll
;                 for (int r = 1; r < 16; ++r) mx = fmaxf(mx, S[r]);
;                 if (first || __any(mx > 8.f)) {
;                     mx = fmaxf(mx, __shfl_xor(mx, 32));
;                     const float dl = first ? mx : fmaxf(mx, 0.f); const float alpha = first ? 1.f : __builtin_amdgcn_exp2f(-dl); negm -= dl; lrun *= alpha; first = false;
; #pragma unroll
;                     for (int r = 0; r < 16; ++r) S[r] -= dl;
; #pragma unroll
;                     for (int j = 0; j < 4; ++j)
; #pragma unroll
;                         for (int r = 0; r < 16; ++r) O[j][r] *= alpha;
;                 }
;                 float ps = 0.f;
; #pragma unroll
;                 for (int r = 0; r < 16; ++r) { S[r] = __builtin_amdgcn_exp2f(S[r]); ps += S[r]; }
;                 lrun += ps;
;                 u32x4 p0, p1;
;                 p0.x = pk2(S[0], S[1]); p0.y = pk2(S[2], S[3]); p0.z = pk2(S[4], S[5]); p0.w = pk2(S[6], S[7]);
;                 p1.x = pk2(S[8], S[9]); p1.y = pk2(S[10], S[11]); p1.z = pk2(S[12], S[13]); p1.w = pk2(S[14], S[15]);
;                 const bf16x8 pa0 = __builtin_bit_cast(bf16x8, p0), pa1 = __builtin_bit_cast(bf16x8, p1);
; #pragma unroll
;                 for (int j = 0; j < 4; ++j) O[j] = MFMA32(vf[2 * j], pa0, O[j]);
; #pragma unroll
;                 for (int j = 0; j < 4; ++j) O[j] = MFMA32(vf[2 * j + 1], pa1, O[j]);
.LBB0_410:
	v_exp_f32_e32 v67, v68
	v_exp_f32_e32 v186, v69
	v_exp_f32_e32 v187, v70
	v_exp_f32_e32 v213, v71
	v_exp_f32_e32 v214, v72
	v_exp_f32_e32 v215, v73
	v_exp_f32_e32 v216, v74
	v_exp_f32_e32 v217, v75
	v_cvt_pk_bf16_f32 v68, v67, v186
	v_cvt_pk_bf16_f32 v69, v187, v213
	v_cvt_pk_bf16_f32 v70, v214, v215
	v_cvt_pk_bf16_f32 v71, v216, v217
	v_add_f32_e32 v67, 0, v67
	v_add_f32_e32 v67, v186, v67
	s_waitcnt lgkmcnt(7)
	v_mfma_f32_32x32x16_bf16 v[50:65], v[140:143], v[68:71], v[50:65]
	v_exp_f32_e32 v76, v76
	v_exp_f32_e32 v77, v77
	v_exp_f32_e32 v78, v78
	v_exp_f32_e32 v79, v79
	v_exp_f32_e32 v80, v80
	v_exp_f32_e32 v81, v81
	v_exp_f32_e32 v82, v82
	s_waitcnt lgkmcnt(5)
	v_mfma_f32_32x32x16_bf16 v[34:49], v[144:147], v[68:71], v[34:49]
	v_exp_f32_e32 v83, v83
	v_add_f32_e32 v67, v187, v67
	v_add_f32_e32 v67, v213, v67
	v_add_f32_e32 v67, v214, v67
	v_add_f32_e32 v67, v215, v67
	v_cvt_pk_bf16_f32 v72, v76, v77
	v_cvt_pk_bf16_f32 v73, v78, v79
	s_waitcnt lgkmcnt(3)
	v_mfma_f32_32x32x16_bf16 v[18:33], v[136:139], v[68:71], v[18:33]
	v_cvt_pk_bf16_f32 v74, v80, v81
	v_cvt_pk_bf16_f32 v75, v82, v83
	v_add_f32_e32 v67, v216, v67
	v_add_f32_e32 v67, v217, v67
	v_add_f32_e32 v67, v76, v67
	v_add_f32_e32 v67, v77, v67
	v_add_f32_e32 v67, v78, v67
	s_waitcnt lgkmcnt(1)
	v_mfma_f32_32x32x16_bf16 v[2:17], v[132:135], v[68:71], v[2:17]
	v_add_f32_e32 v67, v79, v67
	v_add_f32_e32 v67, v80, v67
	v_add_f32_e32 v67, v81, v67
	v_add_f32_e32 v67, v82, v67
	v_add_f32_e32 v67, v83, v67
	v_add_f32_e32 v171, v171, v67
	v_mfma_f32_32x32x16_bf16 v[50:65], v[128:131], v[72:75], v[50:65]
	v_mfma_f32_32x32x16_bf16 v[34:49], v[116:119], v[72:75], v[34:49]
	v_mfma_f32_32x32x16_bf16 v[18:33], v[120:123], v[72:75], v[18:33]
	s_waitcnt lgkmcnt(0)
	v_mfma_f32_32x32x16_bf16 v[2:17], v[124:127], v[72:75], v[2:17]
	ds_read_b128 v[214:217], v185 offset:4608
	ds_read_b128 v[218:221], v185 offset:4640
	ds_read_b128 v[222:225], v185 offset:4672
	ds_read_b128 v[226:229], v185 offset:4704
	ds_read_b128 v[136:139], v184 offset:18496
	ds_read_b128 v[116:119], v184 offset:18528
	ds_read_b128 v[140:143], v184 offset:23104
	ds_read_b128 v[120:123], v184 offset:23136
	ds_read_b128 v[144:147], v184 offset:27712
	ds_read_b128 v[124:127], v184 offset:27744
	ds_read_b128 v[132:135], v184 offset:32320
	ds_read_b128 v[128:131], v184 offset:32352
	s_waitcnt lgkmcnt(11)
	s_nop 0
	v_mfma_f32_32x32x16_bf16 v[68:83], v[214:217], v[84:87], v[230:245]
	s_waitcnt lgkmcnt(10)
	v_mfma_f32_32x32x16_bf16 v[68:83], v[218:221], v[88:91], v[68:83]
	s_waitcnt lgkmcnt(9)
	v_mfma_f32_32x32x16_bf16 v[68:83], v[222:225], v[92:95], v[68:83]
	s_waitcnt lgkmcnt(8)
	v_mfma_f32_32x32x16_bf16 v[68:83], v[226:229], v[96:99], v[68:83]
	s_nop 11
	v_max_f32_e32 v67, v69, v69
	v_max_f32_e32 v184, v68, v68
	v_max_f32_e32 v67, v184, v67
	v_max3_f32 v67, v67, v70, v71
	v_max3_f32 v67, v67, v72, v73
	v_max3_f32 v67, v67, v74, v75
	v_max3_f32 v67, v67, v76, v77
	v_max3_f32 v67, v67, v78, v79
	v_max3_f32 v67, v67, v80, v81
	v_max3_f32 v67, v67, v82, v83
	v_cmp_lt_f32_e32 vcc, s68, v67
	s_cbranch_vccz .LBB0_412
	ds_bpermute_b32 v184, v180, v67
	s_waitcnt lgkmcnt(0)
	v_max3_f32 v184, v67, v184, 0
	v_exp_f32_e64 v186, -v184
	v_sub_f32_e32 v66, v66, v184
	v_mov_b32_e32 v230, v66
	v_mov_b32_e32 v231, v66
	v_mov_b32_e32 v232, v66
	v_mov_b32_e32 v233, v66
	v_mov_b32_e32 v234, v66
	v_mov_b32_e32 v235, v66
	v_mov_b32_e32 v236, v66
	v_mov_b32_e32 v237, v66
	v_mov_b32_e32 v238, v66
	v_mov_b32_e32 v239, v66
	v_mov_b32_e32 v240, v66
	v_mov_b32_e32 v241, v66
	v_mov_b32_e32 v242, v66
	v_mov_b32_e32 v243, v66
	v_mov_b32_e32 v244, v66
	v_mov_b32_e32 v245, v66
	v_pk_add_f32 v[68:69], v[68:69], v[184:185] op_sel_hi:[1,0] neg_lo:[0,1] neg_hi:[0,1]
	v_pk_add_f32 v[70:71], v[70:71], v[184:185] op_sel_hi:[1,0] neg_lo:[0,1] neg_hi:[0,1]
	v_pk_add_f32 v[72:73], v[72:73], v[184:185] op_sel_hi:[1,0] neg_lo:[0,1] neg_hi:[0,1]
	v_pk_add_f32 v[74:75], v[74:75], v[184:185] op_sel_hi:[1,0] neg_lo:[0,1] neg_hi:[0,1]
	v_pk_add_f32 v[76:77], v[76:77], v[184:185] op_sel_hi:[1,0] neg_lo:[0,1] neg_hi:[0,1]
	v_pk_add_f32 v[78:79], v[78:79], v[184:185] op_sel_hi:[1,0] neg_lo:[0,1] neg_hi:[0,1]
	v_pk_add_f32 v[80:81], v[80:81], v[184:185] op_sel_hi:[1,0] neg_lo:[0,1] neg_hi:[0,1]
	v_pk_add_f32 v[82:83], v[82:83], v[184:185] op_sel_hi:[1,0] neg_lo:[0,1] neg_hi:[0,1]
	v_pk_mul_f32 v[64:65], v[64:65], v[186:187] op_sel_hi:[1,0]
	v_pk_mul_f32 v[62:63], v[62:63], v[186:187] op_sel_hi:[1,0]
	v_pk_mul_f32 v[60:61], v[60:61], v[186:187] op_sel_hi:[1,0]
	v_pk_mul_f32 v[58:59], v[58:59], v[186:187] op_sel_hi:[1,0]
	v_pk_mul_f32 v[56:57], v[56:57], v[186:187] op_sel_hi:[1,0]
	v_pk_mul_f32 v[54:55], v[54:55], v[186:187] op_sel_hi:[1,0]
	v_pk_mul_f32 v[52:53], v[52:53], v[186:187] op_sel_hi:[1,0]
	v_pk_mul_f32 v[50:51], v[50:51], v[186:187] op_sel_hi:[1,0]
	v_pk_mul_f32 v[48:49], v[48:49], v[186:187] op_sel_hi:[1,0]
	v_pk_mul_f32 v[46:47], v[46:47], v[186:187] op_sel_hi:[1,0]
	v_pk_mul_f32 v[44:45], v[44:45], v[186:187] op_sel_hi:[1,0]
	v_pk_mul_f32 v[42:43], v[42:43], v[186:187] op_sel_hi:[1,0]
	v_pk_mul_f32 v[40:41], v[40:41], v[186:187] op_sel_hi:[1,0]
	v_pk_mul_f32 v[38:39], v[38:39], v[186:187] op_sel_hi:[1,0]
	v_pk_mul_f32 v[36:37], v[36:37], v[186:187] op_sel_hi:[1,0]
	v_pk_mul_f32 v[34:35], v[34:35], v[186:187] op_sel_hi:[1,0]
	v_pk_mul_f32 v[32:33], v[32:33], v[186:187] op_sel_hi:[1,0]
	v_pk_mul_f32 v[30:31], v[30:31], v[186:187] op_sel_hi:[1,0]
	v_pk_mul_f32 v[28:29], v[28:29], v[186:187] op_sel_hi:[1,0]
	v_pk_mul_f32 v[26:27], v[26:27], v[186:187] op_sel_hi:[1,0]
	v_pk_mul_f32 v[24:25], v[24:25], v[186:187] op_sel_hi:[1,0]
	v_pk_mul_f32 v[22:23], v[22:23], v[186:187] op_sel_hi:[1,0]
	v_pk_mul_f32 v[20:21], v[20:21], v[186:187] op_sel_hi:[1,0]
	v_pk_mul_f32 v[18:19], v[18:19], v[186:187] op_sel_hi:[1,0]
	v_pk_mul_f32 v[16:17], v[16:17], v[186:187] op_sel_hi:[1,0]
	v_pk_mul_f32 v[14:15], v[14:15], v[186:187] op_sel_hi:[1,0]
	v_pk_mul_f32 v[12:13], v[12:13], v[186:187] op_sel_hi:[1,0]
	v_pk_mul_f32 v[10:11], v[10:11], v[186:187] op_sel_hi:[1,0]
	v_pk_mul_f32 v[8:9], v[8:9], v[186:187] op_sel_hi:[1,0]
	v_pk_mul_f32 v[6:7], v[6:7], v[186:187] op_sel_hi:[1,0]
	v_pk_mul_f32 v[4:5], v[4:5], v[186:187] op_sel_hi:[1,0]
	v_pk_mul_f32 v[2:3], v[2:3], v[186:187] op_sel_hi:[1,0]
	v_mul_f32_e32 v171, v171, v186
